# mixers phase A: half the workgroups run the compute items before streaming their FoX pages (HBM streaming overlaps the other half's compute)
# speedup vs baseline: 1.1084x; 1.1084x over previous
.LBB0_316:
	v_readlane_b32 s0, v255, 26
	s_or_b32 s2, s0, 2
	v_readlane_b32 s4, v254, 3
	v_readlane_b32 s5, v254, 4
	s_cmp_le_i32 s4, s2
	s_cselect_b64 s[0:1], -1, 0
	s_cmp_lt_i32 s2, s5
	s_cselect_b64 s[2:3], -1, 0
	s_and_b64 s[0:1], s[0:1], s[2:3]
	s_andn2_b64 vcc, exec, s[0:1]
	s_cbranch_vccnz .LBB0_543
	s_bfe_u32 s101, s92, 0x10003
	s_cmp_eq_u32 s101, 1
	s_cbranch_scc0 .Lma_s1
	s_mov_b32 s101, 2
	s_branch .LBB0_332
.Lma_s1:
	s_mov_b32 s2, s23
	s_getreg_b32 s0, hwreg(HW_REG_HW_ID, 0, 6)
	s_and_b32 s0, s0, 63
	s_lshl_b32 s0, s0, 2
	s_add_i32 s0, s0, 0
	s_add_i32 s0, s0, 0x20400
	v_mov_b32_e32 v0, s0
	ds_read_b32 v2, v0
	v_readlane_b32 s0, v254, 2
	v_mbcnt_lo_u32_b32 v0, -1, 0
	v_mbcnt_hi_u32_b32 v0, -1, v0
	s_and_b32 s4, s0, 7
	s_waitcnt lgkmcnt(0)
	v_readfirstlane_b32 s1, v2
	s_mov_b32 s3, s92
	s_cmp_lg_u32 s4, 0
	v_lshl_add_u32 v2, s1, 6, v0
	s_nop 0
	v_readfirstlane_b32 s1, v2
	s_cbranch_scc1 .LBB0_319
	s_ashr_i32 s5, s3, 31
	s_lshr_b32 s5, s5, 29
	s_add_i32 s5, s3, s5
	s_ashr_i32 s6, s5, 3
	s_and_b32 s5, s5, -8
	s_ashr_i32 s4, s0, 3
	s_sub_i32 s3, s3, s5
	s_mul_i32 s3, s3, s4
	s_add_i32 s3, s3, s6

.LBB0_332:
	s_cmp_eq_u32 s101, 3
	s_cbranch_scc1 .Lma_fin
	s_mov_b32 s6, s23
	s_getreg_b32 s0, hwreg(HW_REG_HW_ID, 0, 6)
	s_and_b32 s0, s0, 63
	s_lshl_b32 s0, s0, 2
	s_add_i32 s0, s0, 0
	s_add_i32 s0, s0, 0x20400
	v_mov_b32_e32 v0, s0
	ds_read_b32 v2, v0
	v_readlane_b32 s0, v254, 2
	s_mov_b32 s2, s0
	v_mbcnt_lo_u32_b32 v0, -1, 0
	v_mbcnt_hi_u32_b32 v0, -1, v0
	s_waitcnt lgkmcnt(0)
	v_readfirstlane_b32 s0, v2
	s_and_b32 s1, s2, 7
	s_mov_b32 s4, s92
	v_lshl_add_u32 v2, s0, 6, v0
	s_cmp_eq_u32 s1, 0
	v_readfirstlane_b32 s0, v2
	s_cbranch_scc0 .LBB0_334
	s_ashr_i32 s3, s4, 31
	s_lshr_b32 s3, s3, 29
	s_add_i32 s3, s4, s3
	s_ashr_i32 s5, s3, 3
	s_and_b32 s3, s3, -8
	s_ashr_i32 s1, s2, 3
	s_sub_i32 s3, s4, s3
	s_mul_i32 s1, s3, s1
	s_add_i32 s4, s1, s5

.LBB0_490:
	s_cmp_eq_u32 s101, 2
	s_cbranch_scc0 .Lma_seam
	v_writelane_b32 v255, s7, 40
	v_writelane_b32 v255, s10, 41
	v_writelane_b32 v255, s11, 42
	v_writelane_b32 v255, s12, 43
	v_writelane_b32 v255, s13, 44
	v_writelane_b32 v255, s16, 45
	v_writelane_b32 v255, s17, 46
	v_writelane_b32 v255, s19, 47
	v_writelane_b32 v255, s20, 48
	v_writelane_b32 v255, s21, 49
	v_writelane_b32 v255, s35, 50
	v_writelane_b32 v255, s36, 51
	v_writelane_b32 v255, s40, 52
	v_writelane_b32 v255, s42, 53
	v_mov_b32_e32 v182, v2
	v_mov_b32_e32 v183, v3
	v_mov_b32_e32 v184, v4
	v_mov_b32_e32 v185, v109
	v_mov_b32_e32 v186, v123
	v_mov_b32_e32 v187, v125
	v_mov_b32_e32 v188, v127
	v_mov_b32_e32 v202, v129
	v_mov_b32_e32 v203, v131
	v_mov_b32_e32 v204, v133
	v_mov_b32_e32 v205, v135
	v_mov_b32_e32 v206, v137
	v_mov_b32_e32 v207, v139
	v_mov_b32_e32 v208, v141
	s_mov_b32 s101, 3
	s_branch .Lma_s1
.Lma_fin:
	v_mov_b32_e32 v2, v182
	v_mov_b32_e32 v3, v183
	v_mov_b32_e32 v4, v184
	v_mov_b32_e32 v109, v185
	v_mov_b32_e32 v123, v186
	v_mov_b32_e32 v125, v187
	v_mov_b32_e32 v127, v188
	v_mov_b32_e32 v129, v202
	v_mov_b32_e32 v131, v203
	v_mov_b32_e32 v133, v204
	v_mov_b32_e32 v135, v205
	v_mov_b32_e32 v137, v206
	v_mov_b32_e32 v139, v207
	v_mov_b32_e32 v141, v208
	v_readlane_b32 s7, v255, 40
	v_readlane_b32 s10, v255, 41
	v_readlane_b32 s11, v255, 42
	v_readlane_b32 s12, v255, 43
	v_readlane_b32 s13, v255, 44
	v_readlane_b32 s16, v255, 45
	v_readlane_b32 s17, v255, 46
	v_readlane_b32 s19, v255, 47
	v_readlane_b32 s20, v255, 48
	v_readlane_b32 s21, v255, 49
	v_readlane_b32 s35, v255, 50
	v_readlane_b32 s36, v255, 51
	v_readlane_b32 s40, v255, 52
	v_readlane_b32 s42, v255, 53
	s_nop 4
	s_mov_b32 s101, 0
